# NSA selected loop: K/V tiles staged by LDS-DMA (global_load_lds_dwordx4, source-side swizzle) into two LDS buffers, one barrier per step, no ds_write
# speedup vs baseline: 1.0284x; 1.0225x over previous
; template <bool FX>
; DI void nsa_tile(const Params& p, int b, int g, int tile, bf16_t* lds, const float CL) {
;     ...
;   for (int hp = 0; hp < 2; ++hp) {
; #pragma unroll
;     for (int hh = 0; hh < 2; ++hh)
; #pragma unroll
;       for (int ks = 0; ks < 2; ++ks) qf[hh][ks] = *(const bf16x8*)(ztok + C_Q + g * 256 + (hp * 2 + hh) * 64 + ks * 32 + quad * 8);
;     st_reset(st);
;     {
;       const bf16_t* kb = zb + C_KS + g * 64;
;       tile64_gload(tid, rk0, rk1, kb, ZS);
;       tile64_gload(tid, rv0, rv1, vsT, TS);
.LBB0_665:
	s_lshl_b32 s28, s6, 8
	v_lshl_add_u64 v[14:15], v[116:117], 0, s[28:29]
	global_load_dwordx4 v[2:5], v[14:15], off
	global_load_dwordx4 v[6:9], v[14:15], off offset:64
	global_load_dwordx4 v[10:13], v[14:15], off offset:128
	s_nop 0
	global_load_dwordx4 v[14:17], v[14:15], off offset:192
	s_nop 0
	v_and_b32_e32 v202, 7, v196
	v_bfe_u32 v218, v196, 4, 3
	v_xor_b32_e32 v202, v202, v218
	v_lshlrev_b32_e32 v202, 4, v202
	v_mov_b32_e32 v203, 0
	v_sub_u32_e32 v218, v202, v0
	v_ashrrev_i32_e32 v219, 31, v218
	v_readfirstlane_b32 s77, v196
	s_lshr_b32 s76, s77, 8
	s_lshl_b32 s76, s76, 16
	s_bfe_u32 s77, s77, 0x20006
	s_lshl_b32 s77, s77, 10
	s_or_b32 s76, s76, s77
	s_or_b32 s76, s76, 0xc000
	s_mov_b32 s75, 0xc000
	s_movk_i32 s78, 0x600
	s_mov_b32 s79, 0
	v_lshl_add_u64 v[58:59], v[132:133], 0, v[218:219]
	v_lshl_add_u64 v[60:61], v[136:137], 0, v[218:219]
	v_lshl_add_u64 v[62:63], v[140:141], 0, v[218:219]
	v_lshl_add_u64 v[64:65], v[144:145], 0, v[218:219]
	v_lshl_add_u64 v[58:59], v[58:59], 0, s[78:79]
	v_lshl_add_u64 v[60:61], v[60:61], 0, s[78:79]
	s_mov_b32 m0, s76
	s_nop 0
	global_load_lds_dwordx4 v[58:59], off
	s_add_u32 m0, s76, 0x1000
	s_nop 0
	global_load_lds_dwordx4 v[60:61], off
	s_add_u32 m0, s76, 0x2000
	s_nop 0
	global_load_lds_dwordx4 v[62:63], off
	s_add_u32 m0, s76, 0x3000
	s_nop 0
	global_load_lds_dwordx4 v[64:65], off
	s_xor_b32 s76, s76, 0xc000
	v_xor_b32_e32 v188, 0xc000, v188
	v_xor_b32_e32 v189, 0xc000, v189
	v_xor_b32_e32 v190, 0xc000, v190
	v_xor_b32_e32 v191, 0xc000, v191
	v_xor_b32_e32 v207, 0xc000, v207
	v_xor_b32_e32 v208, 0xc000, v208
	v_xor_b32_e32 v209, 0xc000, v209
	v_xor_b32_e32 v210, 0xc000, v210
	v_xor_b32_e32 v211, 0xc000, v211
	v_xor_b32_e32 v212, 0xc000, v212
	v_xor_b32_e32 v213, 0xc000, v213
	v_xor_b32_e32 v214, 0xc000, v214
	v_mov_b32_e32 v54, v1
	v_mov_b32_e32 v55, v1
	v_mov_b32_e32 v56, v1
	v_mov_b32_e32 v57, v1
	v_mov_b64_e32 v[46:47], v[54:55]
	v_mov_b64_e32 v[50:51], v[54:55]
	v_mov_b64_e32 v[42:43], v[54:55]
	v_mov_b64_e32 v[38:39], v[54:55]
	v_mov_b64_e32 v[34:35], v[54:55]
	v_mov_b64_e32 v[30:31], v[54:55]
	v_mov_b64_e32 v[26:27], v[54:55]
	v_mov_b64_e32 v[22:23], v[54:55]
	v_mov_b64_e32 v[18:19], v[54:55]
	s_xor_b64 s[36:37], s[2:3], -1
	s_lshl_b32 s7, s6, 7
	s_mov_b32 s28, 64
	s_mov_b32 s68, -1
	v_mov_b32_e32 v187, v185
	v_lshl_add_u64 v[158:159], v[156:157], 0, v[218:219]
	v_lshl_add_u64 v[160:161], v[154:155], 0, v[218:219]
	v_mov_b64_e32 v[48:49], v[56:57]
	v_mov_b64_e32 v[52:53], v[56:57]
	v_mov_b64_e32 v[44:45], v[56:57]
	v_mov_b64_e32 v[40:41], v[56:57]
	v_mov_b64_e32 v[36:37], v[56:57]
	v_mov_b64_e32 v[32:33], v[56:57]
	v_mov_b64_e32 v[28:29], v[56:57]
	v_mov_b64_e32 v[24:25], v[56:57]
	v_mov_b64_e32 v[20:21], v[56:57]
	s_branch .LBB0_668

; template <bool FX>
; DI void nsa_tile(const Params& p, int b, int g, int tile, bf16_t* lds, const float CL) {
;     ...
;       for (int s = 0; s <= cur; ++s) {
;         __syncthreads();
;         tile64_sstore(tid, Ks, rk0, rk1);
;         tile64_sstore(tid, Vs, rv0, rv1);
;         __syncthreads();
;         if (s < cur) {
;           tile64_gload(tid, rk0, rk1, kb + (size_t)(s + 1) * 64 * ZS, ZS);
;           tile64_gload(tid, rv0, rv1, vsT + (s + 1) * 64, TS);
;         }
;         uint32_t wsel = (s < 32) ? sw0 : (s < 64) ? sw1 : (s < 96) ? sw2 : sw3;
;         bool sel = (wsel >> (s & 31)) & 1u;
;         int hi = sel ? (tok - s * 64) : -1;
;         if (__any(hi >= 0)) attn_compute<2, FX>(lane, Ks, Vs, qf, st, invl, 0, hi, dA, dE, CL);
;       }
.LBB0_667:
	s_add_i32 s28, s28, 64
	v_lshl_add_u64 v[160:161], v[160:161], 0, s[22:23]
	v_lshl_add_u64 v[158:159], v[158:159], 0, s[22:23]
	v_xor_b32_e32 v188, 0xc000, v188
	v_xor_b32_e32 v189, 0xc000, v189
	v_xor_b32_e32 v190, 0xc000, v190
	v_xor_b32_e32 v191, 0xc000, v191
	v_xor_b32_e32 v207, 0xc000, v207
	v_xor_b32_e32 v208, 0xc000, v208
	v_xor_b32_e32 v209, 0xc000, v209
	v_xor_b32_e32 v210, 0xc000, v210
	v_xor_b32_e32 v211, 0xc000, v211
	v_xor_b32_e32 v212, 0xc000, v212
	v_xor_b32_e32 v213, 0xc000, v213
	v_xor_b32_e32 v214, 0xc000, v214
	s_xor_b32 s75, s75, 0xc000
	s_cmp_eq_u32 s25, s68
	v_subrev_u32_e32 v187, 64, v187
	s_cbranch_scc1 .LBB0_675
.LBB0_668:
	s_add_i32 s68, s68, 1
	s_waitcnt vmcnt(0)
	s_barrier
	s_cmp_ge_u32 s68, s25
	s_cbranch_scc1 .LBB0_670
	s_lshl_b64 s[2:3], s[28:29], 1
	s_add_u32 s2, s12, s2
	s_addc_u32 s3, s13, s3
	v_lshl_add_u64 v[66:67], v[138:139], 1, s[2:3]
	v_lshl_add_u64 v[68:69], v[142:143], 1, s[2:3]
	v_lshl_add_u64 v[66:67], v[66:67], 0, v[202:203]
	v_lshl_add_u64 v[70:71], v[68:69], 0, v[202:203]
	s_mov_b32 m0, s76
	s_nop 0
	global_load_lds_dwordx4 v[158:159], off
	s_add_u32 m0, s76, 0x1000
	s_nop 0
	global_load_lds_dwordx4 v[160:161], off
	s_add_u32 m0, s76, 0x2000
	s_nop 0
	global_load_lds_dwordx4 v[66:67], off
	s_add_u32 m0, s76, 0x3000
	s_nop 0
	global_load_lds_dwordx4 v[70:71], off
	s_xor_b32 s76, s76, 0xc000

; DI float bf2f(bf16_t h) { return __uint_as_float(((unsigned)h) << 16); }
; DI float sigmoidf(float x) { return __builtin_amdgcn_rcpf(1.f + __expf(-x)); }
; template <bool FX>
; DI void nsa_tile(const Params& p, int b, int g, int tile, bf16_t* lds, const float CL) {
;     ...
;     {
;       float sc[2];
; #pragma unroll
;       for (int h = 0; h < 2; ++h) {
;         float l;
;         if (FX) {
;           l = st.L[h][0];
;         } else {
;           l = st.l[h];
;           l += shx(l, 16, lane);
;           l += shx(l, 32, lane);
;         }
;         sc[h] = (l > 0.f) ? sigmoidf(bf2f(ztok[C_GT + 1 * 8 + g * 4 + hp * 2 + h])) / l : 0.f;
;       }
;       nsa_flush<false>(quad, otok + hp * 128, st, sc);
.LBB0_675:
	v_xor_b32_e32 v188, s75, v188
	v_xor_b32_e32 v189, s75, v189
	v_xor_b32_e32 v190, s75, v190
	v_xor_b32_e32 v191, s75, v191
	v_xor_b32_e32 v207, s75, v207
	v_xor_b32_e32 v208, s75, v208
	v_xor_b32_e32 v209, s75, v209
	v_xor_b32_e32 v210, s75, v210
	v_xor_b32_e32 v211, s75, v211
	v_xor_b32_e32 v212, s75, v212
	v_xor_b32_e32 v213, s75, v213
	v_xor_b32_e32 v214, s75, v214
	s_lshl_b32 s2, s6, 1
	s_or_b32 s70, s2, s21
	v_mov_b32_e32 v48, 0
	v_cmp_lt_f32_e32 vcc, 0, v54
	v_mov_b32_e32 v56, 0
	v_mov_b32_e32 v57, 0
	s_waitcnt vmcnt(3)
	v_mov_b32_e32 v58, 0
	v_mov_b32_e32 v59, 0
	s_and_saveexec_b64 s[2:3], vcc
	s_cbranch_execz .LBB0_677
	s_lshl_b32 s28, s70, 1
	v_lshl_add_u64 v[56:57], v[114:115], 0, s[28:29]
	global_load_ushort v47, v[56:57], off offset:2576
	s_waitcnt vmcnt(0)
	v_lshlrev_b32_e32 v47, 16, v47
	v_mul_f32_e32 v47, 0xbfb8aa3b, v47
	v_exp_f32_e32 v47, v47
	s_nop 0
	v_add_f32_e32 v47, 1.0, v47
	v_rcp_f32_e32 v47, v47
	s_nop 0
	v_div_scale_f32 v49, s[4:5], v54, v54, v47
	v_rcp_f32_e32 v55, v49
	v_div_scale_f32 v56, vcc, v47, v54, v47
	v_fma_f32 v57, -v49, v55, 1.0
	v_fmac_f32_e32 v55, v57, v55
	v_mul_f32_e32 v57, v56, v55
	v_fma_f32 v58, -v49, v57, v56
	v_fmac_f32_e32 v57, v58, v55
	v_fma_f32 v49, -v49, v57, v56
	v_div_fmas_f32 v49, v49, v55, v57
	v_div_fixup_f32 v56, v49, v54, v47
	v_mov_b32_e32 v57, v56
	v_mov_b32_e32 v58, v56
	v_mov_b32_e32 v59, v56
